# GU GEMM SwiGLU epilogue stores made write-through (sc0 sc1) so the grid barrier's L2 write-back has less to flush
# speedup vs baseline: 1.0348x; 1.0051x over previous
.LBB0_398:
	v_lshl_add_u32 v186, s72, 8, v191
	v_ashrrev_i32_e32 v187, 31, v186
	v_lshlrev_b64 v[128:129], 6, v[186:187]
	v_or_b32_e32 v184, 16, v186
	v_lshl_add_u64 v[128:129], v[158:159], 0, v[128:129]
	v_ashrrev_i32_e32 v185, 31, v184
	global_load_dwordx4 v[198:201], v[128:129], off
	v_lshlrev_b64 v[128:129], 6, v[184:185]
	v_lshl_add_u64 v[128:129], v[158:159], 0, v[128:129]
	global_load_dwordx4 v[202:205], v[128:129], off
	v_or_b32_e32 v182, 32, v186
	v_ashrrev_i32_e32 v183, 31, v182
	v_lshlrev_b64 v[128:129], 6, v[182:183]
	v_or_b32_e32 v180, 48, v186
	v_lshl_add_u64 v[128:129], v[158:159], 0, v[128:129]
	v_ashrrev_i32_e32 v181, 31, v180
	global_load_dwordx4 v[148:151], v[128:129], off
	v_lshlrev_b64 v[128:129], 6, v[180:181]
	v_lshl_add_u64 v[128:129], v[158:159], 0, v[128:129]
	global_load_dwordx4 v[144:147], v[128:129], off
	v_add_u32_e32 v178, 0x80, v186
	v_ashrrev_i32_e32 v179, 31, v178
	v_lshlrev_b64 v[128:129], 6, v[178:179]
	v_add_u32_e32 v176, 0x90, v186
	v_lshl_add_u64 v[128:129], v[158:159], 0, v[128:129]
	v_ashrrev_i32_e32 v177, 31, v176
	global_load_dwordx4 v[140:143], v[128:129], off
	v_lshlrev_b64 v[128:129], 6, v[176:177]
	v_lshl_add_u64 v[128:129], v[158:159], 0, v[128:129]
	global_load_dwordx4 v[136:139], v[128:129], off
	v_add_u32_e32 v174, 0xa0, v186
	v_ashrrev_i32_e32 v175, 31, v174
	v_lshlrev_b64 v[128:129], 6, v[174:175]
	v_add_u32_e32 v172, 0xb0, v186
	v_lshl_add_u64 v[128:129], v[158:159], 0, v[128:129]
	v_ashrrev_i32_e32 v173, 31, v172
	global_load_dwordx4 v[132:135], v[128:129], off
	v_lshlrev_b64 v[128:129], 6, v[172:173]
	v_lshl_add_u64 v[128:129], v[158:159], 0, v[128:129]
	global_load_dwordx4 v[128:131], v[128:129], off
	v_and_b32_e32 v175, 64, v208
	v_xor_b32_e32 v173, 16, v208
	v_add_u32_e32 v177, 64, v175
	v_cmp_lt_i32_e32 vcc, v173, v177
	s_mov_b32 s4, 0x358637bd
	v_lshl_or_b32 v188, s10, 7, v196
	v_cndmask_b32_e32 v173, v208, v173, vcc
	v_lshlrev_b32_e32 v175, 2, v173
	v_xor_b32_e32 v173, 32, v208
	v_cmp_lt_i32_e32 vcc, v173, v177
	v_ashrrev_i32_e32 v189, 31, v188
	s_waitcnt vmcnt(0)
	v_mov_b32_e32 v194, v199
	v_mov_b32_e32 v195, v200
	v_mov_b32_e32 v199, v201
	v_pk_add_f32 v[194:195], v[194:195], v[198:199]
	v_mov_b32_e32 v198, v203
	v_mov_b32_e32 v199, v204
	v_mov_b32_e32 v203, v205
	v_pk_add_f32 v[198:199], v[198:199], v[202:203]
	v_mov_b32_e32 v201, v194
	v_mov_b32_e32 v200, v198
	v_mov_b32_e32 v194, v199
	v_pk_add_f32 v[194:195], v[200:201], v[194:195]
	ds_bpermute_b32 v199, v175, v195
	ds_bpermute_b32 v198, v175, v194
	v_cndmask_b32_e32 v173, v208, v173, vcc
	v_lshlrev_b32_e32 v173, 2, v173
	s_waitcnt lgkmcnt(0)
	v_pk_add_f32 v[194:195], v[194:195], v[198:199]
	ds_bpermute_b32 v199, v173, v195
	ds_bpermute_b32 v198, v173, v194
	s_waitcnt lgkmcnt(0)
	v_pk_add_f32 v[198:199], v[194:195], v[198:199]
	v_mov_b64_e32 v[194:195], s[4:5]
	v_pk_fma_f32 v[198:199], v[198:199], s[86:87], v[194:195] op_sel_hi:[1,0,0]
	s_nop 0
	v_mul_f32_e32 v177, 0x4b800000, v199
	v_cmp_gt_f32_e64 s[4:5], s26, v199
	v_cmp_gt_f32_e32 vcc, s26, v198
	s_nop 0
	v_cndmask_b32_e64 v177, v199, v177, s[4:5]
	v_rsq_f32_e32 v177, v177
	v_mov_b32_e32 v199, v150
	v_mov_b32_e32 v150, v145
	v_mov_b32_e32 v145, v147
	v_mul_f32_e32 v179, 0x45800000, v177
	v_cndmask_b32_e64 v192, v177, v179, s[4:5]
	v_mul_f32_e32 v177, 0x4b800000, v198
	v_cndmask_b32_e32 v177, v198, v177, vcc
	v_mov_b32_e32 v198, v149
	v_mov_b32_e32 v149, v151
	v_mov_b32_e32 v151, v146
	v_pk_add_f32 v[148:149], v[198:199], v[148:149]
	v_pk_add_f32 v[144:145], v[150:151], v[144:145]
	v_mov_b32_e32 v147, v148
	v_mov_b32_e32 v146, v144
	v_mov_b32_e32 v148, v145
	v_pk_add_f32 v[144:145], v[146:147], v[148:149]
	ds_bpermute_b32 v147, v175, v145
	ds_bpermute_b32 v146, v175, v144
	v_mov_b32_e32 v148, v141
	v_mov_b32_e32 v149, v142
	v_mov_b32_e32 v141, v143
	v_mov_b32_e32 v142, v137
	v_mov_b32_e32 v143, v138
	v_mov_b32_e32 v137, v139
	v_pk_add_f32 v[140:141], v[148:149], v[140:141]
	v_pk_add_f32 v[136:137], v[142:143], v[136:137]
	s_waitcnt lgkmcnt(0)
	v_pk_add_f32 v[144:145], v[144:145], v[146:147]
	v_mov_b32_e32 v138, v136
	v_mov_b32_e32 v139, v140
	v_mov_b32_e32 v140, v137
	ds_bpermute_b32 v147, v173, v145
	ds_bpermute_b32 v146, v173, v144
	v_pk_add_f32 v[136:137], v[138:139], v[140:141]
	ds_bpermute_b32 v139, v175, v137
	ds_bpermute_b32 v138, v175, v136
	v_mov_b32_e32 v140, v133
	v_mov_b32_e32 v141, v134
	v_mov_b32_e32 v133, v135
	v_mov_b32_e32 v134, v129
	v_mov_b32_e32 v135, v130
	v_mov_b32_e32 v129, v131
	s_waitcnt lgkmcnt(2)
	v_pk_add_f32 v[144:145], v[144:145], v[146:147]
	v_pk_add_f32 v[132:133], v[140:141], v[132:133]
	v_pk_add_f32 v[128:129], v[134:135], v[128:129]
	v_pk_fma_f32 v[144:145], v[144:145], s[86:87], v[194:195] op_sel_hi:[1,0,0]
	s_waitcnt lgkmcnt(0)
	v_pk_add_f32 v[136:137], v[136:137], v[138:139]
	v_mov_b32_e32 v130, v128
	v_mov_b32_e32 v131, v132
	v_mov_b32_e32 v132, v129
	v_mul_f32_e32 v146, 0x4b800000, v145
	v_cmp_gt_f32_e64 s[4:5], s26, v145
	ds_bpermute_b32 v139, v173, v137
	ds_bpermute_b32 v138, v173, v136
	v_pk_add_f32 v[128:129], v[130:131], v[132:133]
	v_cndmask_b32_e64 v145, v145, v146, s[4:5]
	ds_bpermute_b32 v131, v175, v129
	ds_bpermute_b32 v130, v175, v128
	v_rsq_f32_e32 v177, v177
	v_rsq_f32_e32 v145, v145
	s_waitcnt lgkmcnt(2)
	v_pk_add_f32 v[136:137], v[136:137], v[138:139]
	v_pk_mul_f32 v[124:125], v[124:125], v[192:193] op_sel_hi:[1,0]
	v_mul_f32_e32 v179, 0x45800000, v177
	v_mul_f32_e32 v146, 0x45800000, v145
	v_pk_fma_f32 v[136:137], v[136:137], s[86:87], v[194:195] op_sel_hi:[1,0,0]
	s_waitcnt lgkmcnt(0)
	v_pk_add_f32 v[128:129], v[128:129], v[130:131]
	v_cndmask_b32_e32 v190, v177, v179, vcc
	v_cmp_gt_f32_e32 vcc, s26, v144
	v_cndmask_b32_e64 v146, v145, v146, s[4:5]
	v_mul_f32_e32 v145, 0x4b800000, v144
	v_mul_f32_e32 v138, 0x4b800000, v137
	v_cmp_gt_f32_e64 s[4:5], s26, v137
	ds_bpermute_b32 v131, v173, v129
	ds_bpermute_b32 v130, v173, v128
	v_cndmask_b32_e32 v144, v144, v145, vcc
	v_cndmask_b32_e64 v137, v137, v138, s[4:5]
	v_rsq_f32_e32 v144, v144
	v_rsq_f32_e32 v137, v137
	s_waitcnt lgkmcnt(0)
	v_pk_add_f32 v[128:129], v[128:129], v[130:131]
	v_pk_mul_f32 v[116:117], v[116:117], v[192:193] op_sel_hi:[1,0]
	v_mul_f32_e32 v145, 0x45800000, v144
	v_mul_f32_e32 v138, 0x45800000, v137
	v_pk_fma_f32 v[128:129], v[128:129], s[86:87], v[194:195] op_sel_hi:[1,0,0]
	v_cndmask_b32_e32 v144, v144, v145, vcc
	v_cmp_gt_f32_e32 vcc, s26, v136
	v_cndmask_b32_e64 v138, v137, v138, s[4:5]
	v_mul_f32_e32 v137, 0x4b800000, v136
	v_mul_f32_e32 v130, 0x4b800000, v129
	v_cmp_gt_f32_e64 s[4:5], s26, v129
	v_cndmask_b32_e32 v136, v136, v137, vcc
	v_rsq_f32_e32 v136, v136
	v_cndmask_b32_e64 v129, v129, v130, s[4:5]
	v_rsq_f32_e32 v129, v129
	v_pk_mul_f32 v[126:127], v[126:127], v[192:193] op_sel_hi:[1,0]
	v_mul_f32_e32 v137, 0x45800000, v136
	v_cndmask_b32_e32 v136, v136, v137, vcc
	v_mul_f32_e32 v130, 0x45800000, v129
	v_cmp_gt_f32_e32 vcc, s26, v128
	v_cndmask_b32_e64 v130, v129, v130, s[4:5]
	v_mul_f32_e32 v129, 0x4b800000, v128
	v_cndmask_b32_e32 v128, v128, v129, vcc
	v_rsq_f32_e32 v128, v128
	v_pk_mul_f32 v[118:119], v[118:119], v[192:193] op_sel_hi:[1,0]
	v_pk_mul_f32 v[120:121], v[120:121], v[192:193] op_sel_hi:[1,0]
	v_pk_mul_f32 v[112:113], v[112:113], v[192:193] op_sel_hi:[1,0]
	v_mul_f32_e32 v129, 0x45800000, v128
	v_cndmask_b32_e32 v128, v128, v129, vcc
	v_mul_f32_e32 v129, 0xbfb8aa3b, v124
	v_exp_f32_e32 v129, v129
	v_pk_mul_f32 v[122:123], v[122:123], v[192:193] op_sel_hi:[1,0]
	v_pk_mul_f32 v[114:115], v[114:115], v[192:193] op_sel_hi:[1,0]
	v_pk_mul_f32 v[108:109], v[108:109], v[190:191] op_sel_hi:[1,0]
	v_add_f32_e32 v129, 1.0, v129
	v_rcp_f32_e32 v132, v129
	v_mul_f32_e32 v129, 0xbfb8aa3b, v125
	v_exp_f32_e32 v129, v129
	v_pk_mul_f32 v[100:101], v[100:101], v[190:191] op_sel_hi:[1,0]
	v_pk_mul_f32 v[110:111], v[110:111], v[190:191] op_sel_hi:[1,0]
	v_pk_mul_f32 v[102:103], v[102:103], v[190:191] op_sel_hi:[1,0]
	v_add_f32_e32 v129, 1.0, v129
	v_rcp_f32_e32 v133, v129
	v_pk_mul_f32 v[104:105], v[104:105], v[190:191] op_sel_hi:[1,0]
	v_pk_mul_f32 v[106:107], v[106:107], v[190:191] op_sel_hi:[1,0]
	v_pk_mul_f32 v[92:93], v[92:93], v[146:147] op_sel_hi:[1,0]
	v_pk_mul_f32 v[124:125], v[124:125], v[132:133]
	v_pk_mul_f32 v[84:85], v[84:85], v[146:147] op_sel_hi:[1,0]
	v_pk_mul_f32 v[116:117], v[116:117], v[124:125]
	v_pk_mul_f32 v[94:95], v[94:95], v[146:147] op_sel_hi:[1,0]
	v_cvt_pk_bf16_f32 v116, v116, v117
	v_mul_f32_e32 v117, 0xbfb8aa3b, v126
	v_exp_f32_e32 v117, v117
	v_pk_mul_f32 v[86:87], v[86:87], v[146:147] op_sel_hi:[1,0]
	v_pk_mul_f32 v[88:89], v[88:89], v[146:147] op_sel_hi:[1,0]
	v_pk_mul_f32 v[90:91], v[90:91], v[146:147] op_sel_hi:[1,0]
	v_add_f32_e32 v117, 1.0, v117
	v_rcp_f32_e32 v124, v117
	v_mul_f32_e32 v117, 0xbfb8aa3b, v127
	v_exp_f32_e32 v117, v117
	v_pk_mul_f32 v[76:77], v[76:77], v[144:145] op_sel_hi:[1,0]
	v_pk_mul_f32 v[68:69], v[68:69], v[144:145] op_sel_hi:[1,0]
	v_pk_mul_f32 v[78:79], v[78:79], v[144:145] op_sel_hi:[1,0]
	v_add_f32_e32 v117, 1.0, v117
	v_rcp_f32_e32 v125, v117
	v_pk_mul_f32 v[70:71], v[70:71], v[144:145] op_sel_hi:[1,0]
	v_pk_mul_f32 v[72:73], v[72:73], v[144:145] op_sel_hi:[1,0]
	v_pk_mul_f32 v[74:75], v[74:75], v[144:145] op_sel_hi:[1,0]
	v_pk_mul_f32 v[124:125], v[126:127], v[124:125]
	v_pk_mul_f32 v[60:61], v[60:61], v[138:139] op_sel_hi:[1,0]
	v_pk_mul_f32 v[118:119], v[118:119], v[124:125]
	v_pk_mul_f32 v[52:53], v[52:53], v[138:139] op_sel_hi:[1,0]
	v_cvt_pk_bf16_f32 v117, v118, v119
	v_mul_f32_e32 v118, 0xbfb8aa3b, v120
	v_mul_f32_e32 v119, 0xbfb8aa3b, v121
	v_exp_f32_e32 v118, v118
	v_exp_f32_e32 v119, v119
	v_pk_mul_f32 v[62:63], v[62:63], v[138:139] op_sel_hi:[1,0]
	v_pk_mul_f32 v[54:55], v[54:55], v[138:139] op_sel_hi:[1,0]
	v_add_f32_e32 v118, 1.0, v118
	v_add_f32_e32 v119, 1.0, v119
	v_rcp_f32_e32 v118, v118
	v_rcp_f32_e32 v119, v119
	v_pk_mul_f32 v[56:57], v[56:57], v[138:139] op_sel_hi:[1,0]
	v_pk_mul_f32 v[58:59], v[58:59], v[138:139] op_sel_hi:[1,0]
	v_pk_mul_f32 v[44:45], v[44:45], v[136:137] op_sel_hi:[1,0]
	v_pk_mul_f32 v[118:119], v[120:121], v[118:119]
	v_pk_mul_f32 v[36:37], v[36:37], v[136:137] op_sel_hi:[1,0]
	v_pk_mul_f32 v[112:113], v[112:113], v[118:119]
	v_pk_mul_f32 v[46:47], v[46:47], v[136:137] op_sel_hi:[1,0]
	v_cvt_pk_bf16_f32 v118, v112, v113
	v_mul_f32_e32 v112, 0xbfb8aa3b, v122
	v_mul_f32_e32 v113, 0xbfb8aa3b, v123
	v_exp_f32_e32 v112, v112
	v_exp_f32_e32 v113, v113
	v_pk_mul_f32 v[38:39], v[38:39], v[136:137] op_sel_hi:[1,0]
	v_pk_mul_f32 v[40:41], v[40:41], v[136:137] op_sel_hi:[1,0]
	v_add_f32_e32 v112, 1.0, v112
	v_add_f32_e32 v113, 1.0, v113
	v_rcp_f32_e32 v112, v112
	v_rcp_f32_e32 v113, v113
	v_pk_mul_f32 v[42:43], v[42:43], v[136:137] op_sel_hi:[1,0]
	v_pk_mul_f32 v[28:29], v[28:29], v[130:131] op_sel_hi:[1,0]
	v_pk_mul_f32 v[20:21], v[20:21], v[130:131] op_sel_hi:[1,0]
	v_pk_mul_f32 v[112:113], v[122:123], v[112:113]
	v_pk_mul_f32 v[30:31], v[30:31], v[130:131] op_sel_hi:[1,0]
	v_pk_mul_f32 v[112:113], v[114:115], v[112:113]
	v_lshlrev_b64 v[114:115], 1, v[188:189]
	v_cvt_pk_bf16_f32 v119, v112, v113
	v_mov_b64_e32 v[112:113], s[18:19]
	v_mad_i64_i32 v[120:121], s[4:5], v186, s2, v[112:113]
	v_lshl_add_u64 v[120:121], v[120:121], 0, v[114:115]
	global_store_dwordx4 v[120:121], v[116:119], off sc0 sc1
	v_pk_mul_f32 v[22:23], v[22:23], v[130:131] op_sel_hi:[1,0]
	v_pk_mul_f32 v[24:25], v[24:25], v[130:131] op_sel_hi:[1,0]
	v_pk_mul_f32 v[116:117], v[98:99], v[190:191] op_sel_hi:[1,0]
	v_pk_mul_f32 v[98:99], v[96:97], v[190:191] op_sel_hi:[1,0]
	v_mul_f32_e32 v96, 0xbfb8aa3b, v108
	v_mul_f32_e32 v97, 0xbfb8aa3b, v109
	v_exp_f32_e32 v96, v96
	v_exp_f32_e32 v97, v97
	v_pk_mul_f32 v[26:27], v[26:27], v[130:131] op_sel_hi:[1,0]
	v_pk_mul_f32 v[12:13], v[12:13], v[128:129] op_sel_hi:[1,0]
	v_add_f32_e32 v96, 1.0, v96
	v_add_f32_e32 v97, 1.0, v97
	v_rcp_f32_e32 v96, v96
	v_rcp_f32_e32 v97, v97
	v_pk_mul_f32 v[4:5], v[4:5], v[128:129] op_sel_hi:[1,0]
	v_pk_mul_f32 v[14:15], v[14:15], v[128:129] op_sel_hi:[1,0]
	v_pk_mul_f32 v[6:7], v[6:7], v[128:129] op_sel_hi:[1,0]
	v_pk_mul_f32 v[96:97], v[108:109], v[96:97]
	v_pk_mul_f32 v[8:9], v[8:9], v[128:129] op_sel_hi:[1,0]
	v_pk_mul_f32 v[96:97], v[100:101], v[96:97]
	v_pk_mul_f32 v[10:11], v[10:11], v[128:129] op_sel_hi:[1,0]
	v_cvt_pk_bf16_f32 v96, v96, v97
	v_mul_f32_e32 v97, 0xbfb8aa3b, v110
	v_exp_f32_e32 v97, v97
	s_and_b64 vcc, exec, s[38:39]
	v_add_f32_e32 v97, 1.0, v97
	v_rcp_f32_e32 v100, v97
	v_mul_f32_e32 v97, 0xbfb8aa3b, v111
	v_exp_f32_e32 v97, v97
	s_nop 0
	v_add_f32_e32 v97, 1.0, v97
	v_rcp_f32_e32 v101, v97
	s_nop 0
	v_pk_mul_f32 v[100:101], v[110:111], v[100:101]
	s_nop 0
	v_pk_mul_f32 v[100:101], v[102:103], v[100:101]
	s_nop 0
	v_cvt_pk_bf16_f32 v97, v100, v101
	v_mul_f32_e32 v100, 0xbfb8aa3b, v104
	v_mul_f32_e32 v101, 0xbfb8aa3b, v105
	v_exp_f32_e32 v100, v100
	v_exp_f32_e32 v101, v101
	v_add_f32_e32 v100, 1.0, v100
	v_add_f32_e32 v101, 1.0, v101
	v_rcp_f32_e32 v100, v100
	v_rcp_f32_e32 v101, v101
	s_nop 0
	v_pk_mul_f32 v[100:101], v[104:105], v[100:101]
	s_nop 0
	v_pk_mul_f32 v[98:99], v[98:99], v[100:101]
	s_nop 0
	v_cvt_pk_bf16_f32 v98, v98, v99
	v_mul_f32_e32 v99, 0xbfb8aa3b, v106
	v_exp_f32_e32 v99, v99
	s_nop 0
	v_add_f32_e32 v99, 1.0, v99
	v_rcp_f32_e32 v100, v99
	v_mul_f32_e32 v99, 0xbfb8aa3b, v107
	v_exp_f32_e32 v99, v99
	s_nop 0
	v_add_f32_e32 v99, 1.0, v99
	v_rcp_f32_e32 v101, v99
	s_nop 0
	v_pk_mul_f32 v[100:101], v[106:107], v[100:101]
	s_nop 0
	v_pk_mul_f32 v[100:101], v[116:117], v[100:101]
	s_nop 0
	v_cvt_pk_bf16_f32 v99, v100, v101
	v_mad_i64_i32 v[100:101], s[4:5], v184, s2, v[112:113]
	v_lshl_add_u64 v[100:101], v[100:101], 0, v[114:115]
	global_store_dwordx4 v[100:101], v[96:99], off sc0 sc1
	s_nop 1
	v_pk_mul_f32 v[96:97], v[82:83], v[146:147] op_sel_hi:[1,0]
	v_pk_mul_f32 v[82:83], v[80:81], v[146:147] op_sel_hi:[1,0]
	v_mul_f32_e32 v80, 0xbfb8aa3b, v92
	v_mul_f32_e32 v81, 0xbfb8aa3b, v93
	v_exp_f32_e32 v80, v80
	v_exp_f32_e32 v81, v81
	v_add_f32_e32 v80, 1.0, v80
	v_add_f32_e32 v81, 1.0, v81
	v_rcp_f32_e32 v80, v80
	v_rcp_f32_e32 v81, v81
	s_nop 0
	v_pk_mul_f32 v[80:81], v[92:93], v[80:81]
	s_nop 0
	v_pk_mul_f32 v[80:81], v[84:85], v[80:81]
	s_nop 0
	v_cvt_pk_bf16_f32 v80, v80, v81
	v_mul_f32_e32 v81, 0xbfb8aa3b, v94
	v_exp_f32_e32 v81, v81
	s_nop 0
	v_add_f32_e32 v81, 1.0, v81
	v_rcp_f32_e32 v84, v81
	v_mul_f32_e32 v81, 0xbfb8aa3b, v95
	v_exp_f32_e32 v81, v81
	s_nop 0
	v_add_f32_e32 v81, 1.0, v81
	v_rcp_f32_e32 v85, v81
	s_nop 0
	v_pk_mul_f32 v[84:85], v[94:95], v[84:85]
	s_nop 0
	v_pk_mul_f32 v[84:85], v[86:87], v[84:85]
	s_nop 0
	v_cvt_pk_bf16_f32 v81, v84, v85
	v_mul_f32_e32 v84, 0xbfb8aa3b, v88
	v_mul_f32_e32 v85, 0xbfb8aa3b, v89
	v_exp_f32_e32 v84, v84
	v_exp_f32_e32 v85, v85
	v_add_f32_e32 v84, 1.0, v84
	v_add_f32_e32 v85, 1.0, v85
	v_rcp_f32_e32 v84, v84
	v_rcp_f32_e32 v85, v85
	s_nop 0
	v_pk_mul_f32 v[84:85], v[88:89], v[84:85]
	s_nop 0
	v_pk_mul_f32 v[82:83], v[82:83], v[84:85]
	s_nop 0
	v_cvt_pk_bf16_f32 v82, v82, v83
	v_mul_f32_e32 v83, 0xbfb8aa3b, v90
	v_exp_f32_e32 v83, v83
	s_nop 0
	v_add_f32_e32 v83, 1.0, v83
	v_rcp_f32_e32 v84, v83
	v_mul_f32_e32 v83, 0xbfb8aa3b, v91
	v_exp_f32_e32 v83, v83
	s_nop 0
	v_add_f32_e32 v83, 1.0, v83
	v_rcp_f32_e32 v85, v83
	s_nop 0
	v_pk_mul_f32 v[84:85], v[90:91], v[84:85]
	s_nop 0
	v_pk_mul_f32 v[84:85], v[96:97], v[84:85]
	s_nop 0
	v_cvt_pk_bf16_f32 v83, v84, v85
	v_mad_i64_i32 v[84:85], s[4:5], v182, s2, v[112:113]
	v_lshl_add_u64 v[84:85], v[84:85], 0, v[114:115]
	global_store_dwordx4 v[84:85], v[80:83], off sc0 sc1
	s_nop 1
	v_pk_mul_f32 v[80:81], v[66:67], v[144:145] op_sel_hi:[1,0]
	v_pk_mul_f32 v[66:67], v[64:65], v[144:145] op_sel_hi:[1,0]
	v_mul_f32_e32 v64, 0xbfb8aa3b, v76
	v_mul_f32_e32 v65, 0xbfb8aa3b, v77
	v_exp_f32_e32 v64, v64
	v_exp_f32_e32 v65, v65
	v_add_f32_e32 v64, 1.0, v64
	v_add_f32_e32 v65, 1.0, v65
	v_rcp_f32_e32 v64, v64
	v_rcp_f32_e32 v65, v65
	s_nop 0
	v_pk_mul_f32 v[64:65], v[76:77], v[64:65]
	s_nop 0
	v_pk_mul_f32 v[64:65], v[68:69], v[64:65]
	s_nop 0
	v_cvt_pk_bf16_f32 v64, v64, v65
	v_mul_f32_e32 v65, 0xbfb8aa3b, v78
	v_exp_f32_e32 v65, v65
	s_nop 0
	v_add_f32_e32 v65, 1.0, v65
	v_rcp_f32_e32 v68, v65
	v_mul_f32_e32 v65, 0xbfb8aa3b, v79
	v_exp_f32_e32 v65, v65
	s_nop 0
	v_add_f32_e32 v65, 1.0, v65
	v_rcp_f32_e32 v69, v65
	s_nop 0
	v_pk_mul_f32 v[68:69], v[78:79], v[68:69]
	s_nop 0
	v_pk_mul_f32 v[68:69], v[70:71], v[68:69]
	s_nop 0
	v_cvt_pk_bf16_f32 v65, v68, v69
	v_mul_f32_e32 v68, 0xbfb8aa3b, v72
	v_mul_f32_e32 v69, 0xbfb8aa3b, v73
	v_exp_f32_e32 v68, v68
	v_exp_f32_e32 v69, v69
	v_add_f32_e32 v68, 1.0, v68
	v_add_f32_e32 v69, 1.0, v69
	v_rcp_f32_e32 v68, v68
	v_rcp_f32_e32 v69, v69
	s_nop 0
	v_pk_mul_f32 v[68:69], v[72:73], v[68:69]
	s_nop 0
	v_pk_mul_f32 v[66:67], v[66:67], v[68:69]
	s_nop 0
	v_cvt_pk_bf16_f32 v66, v66, v67
	v_mul_f32_e32 v67, 0xbfb8aa3b, v74
	v_exp_f32_e32 v67, v67
	s_nop 0
	v_add_f32_e32 v67, 1.0, v67
	v_rcp_f32_e32 v68, v67
	v_mul_f32_e32 v67, 0xbfb8aa3b, v75
	v_exp_f32_e32 v67, v67
	s_nop 0
	v_add_f32_e32 v67, 1.0, v67
	v_rcp_f32_e32 v69, v67
	s_nop 0
	v_pk_mul_f32 v[68:69], v[74:75], v[68:69]
	s_nop 0
	v_pk_mul_f32 v[68:69], v[80:81], v[68:69]
	s_nop 0
	v_cvt_pk_bf16_f32 v67, v68, v69
	v_mad_i64_i32 v[68:69], s[4:5], v180, s2, v[112:113]
	v_lshl_add_u64 v[68:69], v[68:69], 0, v[114:115]
	global_store_dwordx4 v[68:69], v[64:67], off sc0 sc1
	s_nop 1
	v_pk_mul_f32 v[64:65], v[50:51], v[138:139] op_sel_hi:[1,0]
	v_pk_mul_f32 v[50:51], v[48:49], v[138:139] op_sel_hi:[1,0]
	v_mul_f32_e32 v48, 0xbfb8aa3b, v60
	v_mul_f32_e32 v49, 0xbfb8aa3b, v61
	v_exp_f32_e32 v48, v48
	v_exp_f32_e32 v49, v49
	v_add_f32_e32 v48, 1.0, v48
	v_add_f32_e32 v49, 1.0, v49
	v_rcp_f32_e32 v48, v48
	v_rcp_f32_e32 v49, v49
	s_nop 0
	v_pk_mul_f32 v[48:49], v[60:61], v[48:49]
	s_nop 0
	v_pk_mul_f32 v[48:49], v[52:53], v[48:49]
	s_nop 0
	v_cvt_pk_bf16_f32 v48, v48, v49
	v_mul_f32_e32 v49, 0xbfb8aa3b, v62
	v_exp_f32_e32 v49, v49
	s_nop 0
	v_add_f32_e32 v49, 1.0, v49
	v_rcp_f32_e32 v52, v49
	v_mul_f32_e32 v49, 0xbfb8aa3b, v63
	v_exp_f32_e32 v49, v49
	s_nop 0
	v_add_f32_e32 v49, 1.0, v49
	v_rcp_f32_e32 v53, v49
	s_nop 0
	v_pk_mul_f32 v[52:53], v[62:63], v[52:53]
	s_nop 0
	v_pk_mul_f32 v[52:53], v[54:55], v[52:53]
	s_nop 0
	v_cvt_pk_bf16_f32 v49, v52, v53
	v_mul_f32_e32 v52, 0xbfb8aa3b, v56
	v_mul_f32_e32 v53, 0xbfb8aa3b, v57
	v_exp_f32_e32 v52, v52
	v_exp_f32_e32 v53, v53
	v_add_f32_e32 v52, 1.0, v52
	v_add_f32_e32 v53, 1.0, v53
	v_rcp_f32_e32 v52, v52
	v_rcp_f32_e32 v53, v53
	s_nop 0
	v_pk_mul_f32 v[52:53], v[56:57], v[52:53]
	s_nop 0
	v_pk_mul_f32 v[50:51], v[50:51], v[52:53]
	s_nop 0
	v_cvt_pk_bf16_f32 v50, v50, v51
	v_mul_f32_e32 v51, 0xbfb8aa3b, v58
	v_exp_f32_e32 v51, v51
	s_nop 0
	v_add_f32_e32 v51, 1.0, v51
	v_rcp_f32_e32 v52, v51
	v_mul_f32_e32 v51, 0xbfb8aa3b, v59
	v_exp_f32_e32 v51, v51
	s_nop 0
	v_add_f32_e32 v51, 1.0, v51
	v_rcp_f32_e32 v53, v51
	s_nop 0
	v_pk_mul_f32 v[52:53], v[58:59], v[52:53]
	s_nop 0
	v_pk_mul_f32 v[52:53], v[64:65], v[52:53]
	s_nop 0
	v_cvt_pk_bf16_f32 v51, v52, v53
	v_mad_i64_i32 v[52:53], s[4:5], v178, s2, v[112:113]
	v_lshl_add_u64 v[52:53], v[52:53], 0, v[114:115]
	global_store_dwordx4 v[52:53], v[48:51], off sc0 sc1
	s_nop 1
	v_pk_mul_f32 v[48:49], v[34:35], v[136:137] op_sel_hi:[1,0]
	v_pk_mul_f32 v[34:35], v[32:33], v[136:137] op_sel_hi:[1,0]
	v_mul_f32_e32 v32, 0xbfb8aa3b, v44
	v_mul_f32_e32 v33, 0xbfb8aa3b, v45
	v_exp_f32_e32 v32, v32
	v_exp_f32_e32 v33, v33
	v_add_f32_e32 v32, 1.0, v32
	v_add_f32_e32 v33, 1.0, v33
	v_rcp_f32_e32 v32, v32
	v_rcp_f32_e32 v33, v33
	s_nop 0
	v_pk_mul_f32 v[32:33], v[44:45], v[32:33]
	s_nop 0
	v_pk_mul_f32 v[32:33], v[36:37], v[32:33]
	s_nop 0
	v_cvt_pk_bf16_f32 v32, v32, v33
	v_mul_f32_e32 v33, 0xbfb8aa3b, v46
	v_exp_f32_e32 v33, v33
	s_nop 0
	v_add_f32_e32 v33, 1.0, v33
	v_rcp_f32_e32 v36, v33
	v_mul_f32_e32 v33, 0xbfb8aa3b, v47
	v_exp_f32_e32 v33, v33
	s_nop 0
	v_add_f32_e32 v33, 1.0, v33
	v_rcp_f32_e32 v37, v33
	s_nop 0
	v_pk_mul_f32 v[36:37], v[46:47], v[36:37]
	s_nop 0
	v_pk_mul_f32 v[36:37], v[38:39], v[36:37]
	s_nop 0
	v_cvt_pk_bf16_f32 v33, v36, v37
	v_mul_f32_e32 v36, 0xbfb8aa3b, v40
	v_mul_f32_e32 v37, 0xbfb8aa3b, v41
	v_exp_f32_e32 v36, v36
	v_exp_f32_e32 v37, v37
	v_add_f32_e32 v36, 1.0, v36
	v_add_f32_e32 v37, 1.0, v37
	v_rcp_f32_e32 v36, v36
	v_rcp_f32_e32 v37, v37
	s_nop 0
	v_pk_mul_f32 v[36:37], v[40:41], v[36:37]
	s_nop 0
	v_pk_mul_f32 v[34:35], v[34:35], v[36:37]
	s_nop 0
	v_cvt_pk_bf16_f32 v34, v34, v35
	v_mul_f32_e32 v35, 0xbfb8aa3b, v42
	v_exp_f32_e32 v35, v35
	s_nop 0
	v_add_f32_e32 v35, 1.0, v35
	v_rcp_f32_e32 v36, v35
	v_mul_f32_e32 v35, 0xbfb8aa3b, v43
	v_exp_f32_e32 v35, v35
	s_nop 0
	v_add_f32_e32 v35, 1.0, v35
	v_rcp_f32_e32 v37, v35
	s_nop 0
	v_pk_mul_f32 v[36:37], v[42:43], v[36:37]
	s_nop 0
	v_pk_mul_f32 v[36:37], v[48:49], v[36:37]
	s_nop 0
	v_cvt_pk_bf16_f32 v35, v36, v37
	v_mad_i64_i32 v[36:37], s[4:5], v176, s2, v[112:113]
	v_lshl_add_u64 v[36:37], v[36:37], 0, v[114:115]
	global_store_dwordx4 v[36:37], v[32:35], off sc0 sc1
	s_nop 1
	v_pk_mul_f32 v[32:33], v[18:19], v[130:131] op_sel_hi:[1,0]
	v_pk_mul_f32 v[18:19], v[16:17], v[130:131] op_sel_hi:[1,0]
	v_mul_f32_e32 v16, 0xbfb8aa3b, v28
	v_mul_f32_e32 v17, 0xbfb8aa3b, v29
	v_exp_f32_e32 v16, v16
	v_exp_f32_e32 v17, v17
	v_add_f32_e32 v16, 1.0, v16
	v_add_f32_e32 v17, 1.0, v17
	v_rcp_f32_e32 v16, v16
	v_rcp_f32_e32 v17, v17
	s_nop 0
	v_pk_mul_f32 v[16:17], v[28:29], v[16:17]
	s_nop 0
	v_pk_mul_f32 v[16:17], v[20:21], v[16:17]
	s_nop 0
	v_cvt_pk_bf16_f32 v16, v16, v17
	v_mul_f32_e32 v17, 0xbfb8aa3b, v30
	v_exp_f32_e32 v17, v17
	s_nop 0
	v_add_f32_e32 v17, 1.0, v17
	v_rcp_f32_e32 v20, v17
	v_mul_f32_e32 v17, 0xbfb8aa3b, v31
	v_exp_f32_e32 v17, v17
	s_nop 0
	v_add_f32_e32 v17, 1.0, v17
	v_rcp_f32_e32 v21, v17
	s_nop 0
	v_pk_mul_f32 v[20:21], v[30:31], v[20:21]
	s_nop 0
	v_pk_mul_f32 v[20:21], v[22:23], v[20:21]
	s_nop 0
	v_cvt_pk_bf16_f32 v17, v20, v21
	v_mul_f32_e32 v20, 0xbfb8aa3b, v24
	v_mul_f32_e32 v21, 0xbfb8aa3b, v25
	v_exp_f32_e32 v20, v20
	v_exp_f32_e32 v21, v21
	v_add_f32_e32 v20, 1.0, v20
	v_add_f32_e32 v21, 1.0, v21
	v_rcp_f32_e32 v20, v20
	v_rcp_f32_e32 v21, v21
	s_nop 0
	v_pk_mul_f32 v[20:21], v[24:25], v[20:21]
	s_nop 0
	v_pk_mul_f32 v[18:19], v[18:19], v[20:21]
	s_nop 0
	v_cvt_pk_bf16_f32 v18, v18, v19
	v_mul_f32_e32 v19, 0xbfb8aa3b, v26
	v_exp_f32_e32 v19, v19
	s_nop 0
	v_add_f32_e32 v19, 1.0, v19
	v_rcp_f32_e32 v20, v19
	v_mul_f32_e32 v19, 0xbfb8aa3b, v27
	v_exp_f32_e32 v19, v19
	s_nop 0
	v_add_f32_e32 v19, 1.0, v19
	v_rcp_f32_e32 v21, v19
	s_nop 0
	v_pk_mul_f32 v[20:21], v[26:27], v[20:21]
	s_nop 0
	v_pk_mul_f32 v[20:21], v[32:33], v[20:21]
	s_nop 0
	v_cvt_pk_bf16_f32 v19, v20, v21
	v_mad_i64_i32 v[20:21], s[4:5], v174, s2, v[112:113]
	v_lshl_add_u64 v[20:21], v[20:21], 0, v[114:115]
	global_store_dwordx4 v[20:21], v[16:19], off sc0 sc1
	s_nop 1
	v_pk_mul_f32 v[16:17], v[2:3], v[128:129] op_sel_hi:[1,0]
	v_pk_mul_f32 v[2:3], v[0:1], v[128:129] op_sel_hi:[1,0]
	v_mul_f32_e32 v0, 0xbfb8aa3b, v12
	v_mul_f32_e32 v1, 0xbfb8aa3b, v13
	v_exp_f32_e32 v0, v0
	v_exp_f32_e32 v1, v1
	v_add_f32_e32 v0, 1.0, v0
	v_add_f32_e32 v1, 1.0, v1
	v_rcp_f32_e32 v0, v0
	v_rcp_f32_e32 v1, v1
	s_nop 0
	v_pk_mul_f32 v[0:1], v[12:13], v[0:1]
	s_nop 0
	v_pk_mul_f32 v[0:1], v[4:5], v[0:1]
	s_nop 0
	v_cvt_pk_bf16_f32 v0, v0, v1
	v_mul_f32_e32 v1, 0xbfb8aa3b, v14
	v_exp_f32_e32 v1, v1
	s_nop 0
	v_add_f32_e32 v1, 1.0, v1
	v_rcp_f32_e32 v4, v1
	v_mul_f32_e32 v1, 0xbfb8aa3b, v15
	v_exp_f32_e32 v1, v1
	s_nop 0
	v_add_f32_e32 v1, 1.0, v1
	v_rcp_f32_e32 v5, v1
	s_nop 0
	v_pk_mul_f32 v[4:5], v[14:15], v[4:5]
	s_nop 0
	v_pk_mul_f32 v[4:5], v[6:7], v[4:5]
	s_nop 0
	v_cvt_pk_bf16_f32 v1, v4, v5
	v_mul_f32_e32 v4, 0xbfb8aa3b, v8
	v_mul_f32_e32 v5, 0xbfb8aa3b, v9
	v_exp_f32_e32 v4, v4
	v_exp_f32_e32 v5, v5
	v_add_f32_e32 v4, 1.0, v4
	v_add_f32_e32 v5, 1.0, v5
	v_rcp_f32_e32 v4, v4
	v_rcp_f32_e32 v5, v5
	s_nop 0
	v_pk_mul_f32 v[4:5], v[8:9], v[4:5]
	s_nop 0
	v_pk_mul_f32 v[2:3], v[2:3], v[4:5]
	s_nop 0
	v_cvt_pk_bf16_f32 v2, v2, v3
	v_mul_f32_e32 v3, 0xbfb8aa3b, v10
	v_exp_f32_e32 v3, v3
	s_nop 0
	v_add_f32_e32 v3, 1.0, v3
	v_rcp_f32_e32 v4, v3
	v_mul_f32_e32 v3, 0xbfb8aa3b, v11
	v_exp_f32_e32 v3, v3
	s_nop 0
	v_add_f32_e32 v3, 1.0, v3
	v_rcp_f32_e32 v5, v3
	s_nop 0
	v_pk_mul_f32 v[4:5], v[10:11], v[4:5]
	s_nop 0
	v_pk_mul_f32 v[4:5], v[16:17], v[4:5]
	s_nop 0
	v_cvt_pk_bf16_f32 v3, v4, v5
	v_mad_i64_i32 v[4:5], s[4:5], v172, s2, v[112:113]
	v_lshl_add_u64 v[4:5], v[4:5], 0, v[114:115]
	s_mov_b64 s[4:5], -1
	global_store_dwordx4 v[4:5], v[0:3], off sc0 sc1
	s_cbranch_vccnz .LBB0_382
	s_andn2_b64 vcc, exec, s[16:17]
	s_cbranch_vccnz .LBB0_381
	s_barrier
	s_branch .LBB0_381

.LBB0_2087:
	v_lshl_add_u32 v184, s72, 8, v189
	v_ashrrev_i32_e32 v185, 31, v184
	v_lshlrev_b64 v[128:129], 6, v[184:185]
	v_or_b32_e32 v182, 16, v184
	v_lshl_add_u64 v[128:129], v[158:159], 0, v[128:129]
	v_ashrrev_i32_e32 v183, 31, v182
	global_load_dwordx4 v[196:199], v[128:129], off
	v_lshlrev_b64 v[128:129], 6, v[182:183]
	v_lshl_add_u64 v[128:129], v[158:159], 0, v[128:129]
	global_load_dwordx4 v[200:203], v[128:129], off
	v_or_b32_e32 v180, 32, v184
	v_ashrrev_i32_e32 v181, 31, v180
	v_lshlrev_b64 v[128:129], 6, v[180:181]
	v_or_b32_e32 v178, 48, v184
	v_lshl_add_u64 v[128:129], v[158:159], 0, v[128:129]
	v_ashrrev_i32_e32 v179, 31, v178
	global_load_dwordx4 v[148:151], v[128:129], off
	v_lshlrev_b64 v[128:129], 6, v[178:179]
	v_lshl_add_u64 v[128:129], v[158:159], 0, v[128:129]
	global_load_dwordx4 v[144:147], v[128:129], off
	v_add_u32_e32 v176, 0x80, v184
	v_ashrrev_i32_e32 v177, 31, v176
	v_lshlrev_b64 v[128:129], 6, v[176:177]
	v_add_u32_e32 v174, 0x90, v184
	v_lshl_add_u64 v[128:129], v[158:159], 0, v[128:129]
	v_ashrrev_i32_e32 v175, 31, v174
	global_load_dwordx4 v[140:143], v[128:129], off
	v_lshlrev_b64 v[128:129], 6, v[174:175]
	v_lshl_add_u64 v[128:129], v[158:159], 0, v[128:129]
	global_load_dwordx4 v[136:139], v[128:129], off
	v_add_u32_e32 v172, 0xa0, v184
	v_ashrrev_i32_e32 v173, 31, v172
	v_lshlrev_b64 v[128:129], 6, v[172:173]
	v_add_u32_e32 v170, 0xb0, v184
	v_lshl_add_u64 v[128:129], v[158:159], 0, v[128:129]
	v_ashrrev_i32_e32 v171, 31, v170
	global_load_dwordx4 v[132:135], v[128:129], off
	v_lshlrev_b64 v[128:129], 6, v[170:171]
	v_lshl_add_u64 v[128:129], v[158:159], 0, v[128:129]
	global_load_dwordx4 v[128:131], v[128:129], off
	v_and_b32_e32 v173, 64, v208
	v_xor_b32_e32 v171, 16, v208
	v_add_u32_e32 v175, 64, v173
	v_cmp_lt_i32_e32 vcc, v171, v175
	s_mov_b32 s0, 0x358637bd
	v_lshl_or_b32 v186, s10, 7, v194
	v_cndmask_b32_e32 v171, v208, v171, vcc
	v_lshlrev_b32_e32 v173, 2, v171
	v_xor_b32_e32 v171, 32, v208
	v_cmp_lt_i32_e32 vcc, v171, v175
	v_ashrrev_i32_e32 v187, 31, v186
	s_waitcnt vmcnt(0)
	v_mov_b32_e32 v192, v197
	v_mov_b32_e32 v193, v198
	v_mov_b32_e32 v197, v199
	v_pk_add_f32 v[192:193], v[192:193], v[196:197]
	v_mov_b32_e32 v196, v201
	v_mov_b32_e32 v197, v202
	v_mov_b32_e32 v201, v203
	v_pk_add_f32 v[196:197], v[196:197], v[200:201]
	v_mov_b32_e32 v199, v192
	v_mov_b32_e32 v198, v196
	v_mov_b32_e32 v192, v197
	v_pk_add_f32 v[192:193], v[198:199], v[192:193]
	ds_bpermute_b32 v197, v173, v193
	ds_bpermute_b32 v196, v173, v192
	v_cndmask_b32_e32 v171, v208, v171, vcc
	v_lshlrev_b32_e32 v171, 2, v171
	s_waitcnt lgkmcnt(0)
	v_pk_add_f32 v[192:193], v[192:193], v[196:197]
	ds_bpermute_b32 v197, v171, v193
	ds_bpermute_b32 v196, v171, v192
	s_waitcnt lgkmcnt(0)
	v_pk_add_f32 v[196:197], v[192:193], v[196:197]
	v_mov_b64_e32 v[192:193], s[0:1]
	v_pk_fma_f32 v[196:197], v[196:197], s[86:87], v[192:193] op_sel_hi:[1,0,0]
	s_nop 0
	v_mul_f32_e32 v175, 0x4b800000, v197
	v_cmp_gt_f32_e64 s[0:1], s26, v197
	v_cmp_gt_f32_e32 vcc, s26, v196
	s_nop 0
	v_cndmask_b32_e64 v175, v197, v175, s[0:1]
	v_rsq_f32_e32 v175, v175
	v_mov_b32_e32 v197, v150
	v_mov_b32_e32 v150, v145
	v_mov_b32_e32 v145, v147
	v_mul_f32_e32 v177, 0x45800000, v175
	v_cndmask_b32_e64 v190, v175, v177, s[0:1]
	v_mul_f32_e32 v175, 0x4b800000, v196
	v_cndmask_b32_e32 v175, v196, v175, vcc
	v_mov_b32_e32 v196, v149
	v_mov_b32_e32 v149, v151
	v_mov_b32_e32 v151, v146
	v_pk_add_f32 v[148:149], v[196:197], v[148:149]
	v_pk_add_f32 v[144:145], v[150:151], v[144:145]
	v_mov_b32_e32 v147, v148
	v_mov_b32_e32 v146, v144
	v_mov_b32_e32 v148, v145
	v_pk_add_f32 v[144:145], v[146:147], v[148:149]
	ds_bpermute_b32 v147, v173, v145
	ds_bpermute_b32 v146, v173, v144
	v_mov_b32_e32 v148, v141
	v_mov_b32_e32 v149, v142
	v_mov_b32_e32 v141, v143
	v_mov_b32_e32 v142, v137
	v_mov_b32_e32 v143, v138
	v_mov_b32_e32 v137, v139
	v_pk_add_f32 v[140:141], v[148:149], v[140:141]
	v_pk_add_f32 v[136:137], v[142:143], v[136:137]
	s_waitcnt lgkmcnt(0)
	v_pk_add_f32 v[144:145], v[144:145], v[146:147]
	v_mov_b32_e32 v138, v136
	v_mov_b32_e32 v139, v140
	v_mov_b32_e32 v140, v137
	ds_bpermute_b32 v147, v171, v145
	ds_bpermute_b32 v146, v171, v144
	v_pk_add_f32 v[136:137], v[138:139], v[140:141]
	ds_bpermute_b32 v139, v173, v137
	ds_bpermute_b32 v138, v173, v136
	v_mov_b32_e32 v140, v133
	v_mov_b32_e32 v141, v134
	v_mov_b32_e32 v133, v135
	v_mov_b32_e32 v134, v129
	v_mov_b32_e32 v135, v130
	v_mov_b32_e32 v129, v131
	s_waitcnt lgkmcnt(2)
	v_pk_add_f32 v[144:145], v[144:145], v[146:147]
	v_pk_add_f32 v[132:133], v[140:141], v[132:133]
	v_pk_add_f32 v[128:129], v[134:135], v[128:129]
	v_pk_fma_f32 v[144:145], v[144:145], s[86:87], v[192:193] op_sel_hi:[1,0,0]
	s_waitcnt lgkmcnt(0)
	v_pk_add_f32 v[136:137], v[136:137], v[138:139]
	v_mov_b32_e32 v130, v128
	v_mov_b32_e32 v131, v132
	v_mov_b32_e32 v132, v129
	v_mul_f32_e32 v146, 0x4b800000, v145
	v_cmp_gt_f32_e64 s[0:1], s26, v145
	ds_bpermute_b32 v139, v171, v137
	ds_bpermute_b32 v138, v171, v136
	v_pk_add_f32 v[128:129], v[130:131], v[132:133]
	v_cndmask_b32_e64 v145, v145, v146, s[0:1]
	ds_bpermute_b32 v131, v173, v129
	ds_bpermute_b32 v130, v173, v128
	v_rsq_f32_e32 v175, v175
	v_rsq_f32_e32 v145, v145
	s_waitcnt lgkmcnt(2)
	v_pk_add_f32 v[136:137], v[136:137], v[138:139]
	v_pk_mul_f32 v[124:125], v[124:125], v[190:191] op_sel_hi:[1,0]
	v_mul_f32_e32 v177, 0x45800000, v175
	v_mul_f32_e32 v146, 0x45800000, v145
	v_pk_fma_f32 v[136:137], v[136:137], s[86:87], v[192:193] op_sel_hi:[1,0,0]
	s_waitcnt lgkmcnt(0)
	v_pk_add_f32 v[128:129], v[128:129], v[130:131]
	v_cndmask_b32_e32 v188, v175, v177, vcc
	v_cmp_gt_f32_e32 vcc, s26, v144
	v_cndmask_b32_e64 v146, v145, v146, s[0:1]
	v_mul_f32_e32 v145, 0x4b800000, v144
	v_mul_f32_e32 v138, 0x4b800000, v137
	v_cmp_gt_f32_e64 s[0:1], s26, v137
	ds_bpermute_b32 v131, v171, v129
	ds_bpermute_b32 v130, v171, v128
	v_cndmask_b32_e32 v144, v144, v145, vcc
	v_cndmask_b32_e64 v137, v137, v138, s[0:1]
	v_rsq_f32_e32 v144, v144
	v_rsq_f32_e32 v137, v137
	s_waitcnt lgkmcnt(0)
	v_pk_add_f32 v[128:129], v[128:129], v[130:131]
	v_pk_mul_f32 v[116:117], v[116:117], v[190:191] op_sel_hi:[1,0]
	v_mul_f32_e32 v145, 0x45800000, v144
	v_mul_f32_e32 v138, 0x45800000, v137
	v_pk_fma_f32 v[128:129], v[128:129], s[86:87], v[192:193] op_sel_hi:[1,0,0]
	v_cndmask_b32_e32 v144, v144, v145, vcc
	v_cmp_gt_f32_e32 vcc, s26, v136
	v_cndmask_b32_e64 v138, v137, v138, s[0:1]
	v_mul_f32_e32 v137, 0x4b800000, v136
	v_mul_f32_e32 v130, 0x4b800000, v129
	v_cmp_gt_f32_e64 s[0:1], s26, v129
	v_cndmask_b32_e32 v136, v136, v137, vcc
	v_rsq_f32_e32 v136, v136
	v_cndmask_b32_e64 v129, v129, v130, s[0:1]
	v_rsq_f32_e32 v129, v129
	v_pk_mul_f32 v[126:127], v[126:127], v[190:191] op_sel_hi:[1,0]
	v_mul_f32_e32 v137, 0x45800000, v136
	v_cndmask_b32_e32 v136, v136, v137, vcc
	v_mul_f32_e32 v130, 0x45800000, v129
	v_cmp_gt_f32_e32 vcc, s26, v128
	v_cndmask_b32_e64 v130, v129, v130, s[0:1]
	v_mul_f32_e32 v129, 0x4b800000, v128
	v_cndmask_b32_e32 v128, v128, v129, vcc
	v_rsq_f32_e32 v128, v128
	v_pk_mul_f32 v[118:119], v[118:119], v[190:191] op_sel_hi:[1,0]
	v_pk_mul_f32 v[120:121], v[120:121], v[190:191] op_sel_hi:[1,0]
	v_pk_mul_f32 v[112:113], v[112:113], v[190:191] op_sel_hi:[1,0]
	v_mul_f32_e32 v129, 0x45800000, v128
	v_cndmask_b32_e32 v128, v128, v129, vcc
	v_mul_f32_e32 v129, 0xbfb8aa3b, v124
	v_exp_f32_e32 v129, v129
	v_pk_mul_f32 v[122:123], v[122:123], v[190:191] op_sel_hi:[1,0]
	v_pk_mul_f32 v[114:115], v[114:115], v[190:191] op_sel_hi:[1,0]
	v_pk_mul_f32 v[108:109], v[108:109], v[188:189] op_sel_hi:[1,0]
	v_add_f32_e32 v129, 1.0, v129
	v_rcp_f32_e32 v132, v129
	v_mul_f32_e32 v129, 0xbfb8aa3b, v125
	v_exp_f32_e32 v129, v129
	v_pk_mul_f32 v[100:101], v[100:101], v[188:189] op_sel_hi:[1,0]
	v_pk_mul_f32 v[110:111], v[110:111], v[188:189] op_sel_hi:[1,0]
	v_pk_mul_f32 v[102:103], v[102:103], v[188:189] op_sel_hi:[1,0]
	v_add_f32_e32 v129, 1.0, v129
	v_rcp_f32_e32 v133, v129
	v_pk_mul_f32 v[104:105], v[104:105], v[188:189] op_sel_hi:[1,0]
	v_pk_mul_f32 v[106:107], v[106:107], v[188:189] op_sel_hi:[1,0]
	v_pk_mul_f32 v[92:93], v[92:93], v[146:147] op_sel_hi:[1,0]
	v_pk_mul_f32 v[124:125], v[124:125], v[132:133]
	v_pk_mul_f32 v[84:85], v[84:85], v[146:147] op_sel_hi:[1,0]
	v_pk_mul_f32 v[116:117], v[116:117], v[124:125]
	v_pk_mul_f32 v[94:95], v[94:95], v[146:147] op_sel_hi:[1,0]
	v_cvt_pk_bf16_f32 v116, v116, v117
	v_mul_f32_e32 v117, 0xbfb8aa3b, v126
	v_exp_f32_e32 v117, v117
	v_pk_mul_f32 v[86:87], v[86:87], v[146:147] op_sel_hi:[1,0]
	v_pk_mul_f32 v[88:89], v[88:89], v[146:147] op_sel_hi:[1,0]
	v_pk_mul_f32 v[90:91], v[90:91], v[146:147] op_sel_hi:[1,0]
	v_add_f32_e32 v117, 1.0, v117
	v_rcp_f32_e32 v124, v117
	v_mul_f32_e32 v117, 0xbfb8aa3b, v127
	v_exp_f32_e32 v117, v117
	v_pk_mul_f32 v[76:77], v[76:77], v[144:145] op_sel_hi:[1,0]
	v_pk_mul_f32 v[68:69], v[68:69], v[144:145] op_sel_hi:[1,0]
	v_pk_mul_f32 v[78:79], v[78:79], v[144:145] op_sel_hi:[1,0]
	v_add_f32_e32 v117, 1.0, v117
	v_rcp_f32_e32 v125, v117
	v_pk_mul_f32 v[70:71], v[70:71], v[144:145] op_sel_hi:[1,0]
	v_pk_mul_f32 v[72:73], v[72:73], v[144:145] op_sel_hi:[1,0]
	v_pk_mul_f32 v[74:75], v[74:75], v[144:145] op_sel_hi:[1,0]
	v_pk_mul_f32 v[124:125], v[126:127], v[124:125]
	v_pk_mul_f32 v[60:61], v[60:61], v[138:139] op_sel_hi:[1,0]
	v_pk_mul_f32 v[118:119], v[118:119], v[124:125]
	v_pk_mul_f32 v[52:53], v[52:53], v[138:139] op_sel_hi:[1,0]
	v_cvt_pk_bf16_f32 v117, v118, v119
	v_mul_f32_e32 v118, 0xbfb8aa3b, v120
	v_mul_f32_e32 v119, 0xbfb8aa3b, v121
	v_exp_f32_e32 v118, v118
	v_exp_f32_e32 v119, v119
	v_pk_mul_f32 v[62:63], v[62:63], v[138:139] op_sel_hi:[1,0]
	v_pk_mul_f32 v[54:55], v[54:55], v[138:139] op_sel_hi:[1,0]
	v_add_f32_e32 v118, 1.0, v118
	v_add_f32_e32 v119, 1.0, v119
	v_rcp_f32_e32 v118, v118
	v_rcp_f32_e32 v119, v119
	v_pk_mul_f32 v[56:57], v[56:57], v[138:139] op_sel_hi:[1,0]
	v_pk_mul_f32 v[58:59], v[58:59], v[138:139] op_sel_hi:[1,0]
	v_pk_mul_f32 v[44:45], v[44:45], v[136:137] op_sel_hi:[1,0]
	v_pk_mul_f32 v[118:119], v[120:121], v[118:119]
	v_pk_mul_f32 v[36:37], v[36:37], v[136:137] op_sel_hi:[1,0]
	v_pk_mul_f32 v[112:113], v[112:113], v[118:119]
	v_pk_mul_f32 v[46:47], v[46:47], v[136:137] op_sel_hi:[1,0]
	v_cvt_pk_bf16_f32 v118, v112, v113
	v_mul_f32_e32 v112, 0xbfb8aa3b, v122
	v_mul_f32_e32 v113, 0xbfb8aa3b, v123
	v_exp_f32_e32 v112, v112
	v_exp_f32_e32 v113, v113
	v_pk_mul_f32 v[38:39], v[38:39], v[136:137] op_sel_hi:[1,0]
	v_pk_mul_f32 v[40:41], v[40:41], v[136:137] op_sel_hi:[1,0]
	v_add_f32_e32 v112, 1.0, v112
	v_add_f32_e32 v113, 1.0, v113
	v_rcp_f32_e32 v112, v112
	v_rcp_f32_e32 v113, v113
	v_pk_mul_f32 v[42:43], v[42:43], v[136:137] op_sel_hi:[1,0]
	v_pk_mul_f32 v[28:29], v[28:29], v[130:131] op_sel_hi:[1,0]
	v_pk_mul_f32 v[20:21], v[20:21], v[130:131] op_sel_hi:[1,0]
	v_pk_mul_f32 v[112:113], v[122:123], v[112:113]
	v_pk_mul_f32 v[30:31], v[30:31], v[130:131] op_sel_hi:[1,0]
	v_pk_mul_f32 v[112:113], v[114:115], v[112:113]
	v_lshlrev_b64 v[114:115], 1, v[186:187]
	v_cvt_pk_bf16_f32 v119, v112, v113
	v_mov_b64_e32 v[112:113], s[22:23]
	v_mad_i64_i32 v[120:121], s[0:1], v184, s2, v[112:113]
	v_lshl_add_u64 v[120:121], v[120:121], 0, v[114:115]
	global_store_dwordx4 v[120:121], v[116:119], off sc0 sc1
	v_pk_mul_f32 v[22:23], v[22:23], v[130:131] op_sel_hi:[1,0]
	v_pk_mul_f32 v[24:25], v[24:25], v[130:131] op_sel_hi:[1,0]
	v_pk_mul_f32 v[116:117], v[98:99], v[188:189] op_sel_hi:[1,0]
	v_pk_mul_f32 v[98:99], v[96:97], v[188:189] op_sel_hi:[1,0]
	v_mul_f32_e32 v96, 0xbfb8aa3b, v108
	v_mul_f32_e32 v97, 0xbfb8aa3b, v109
	v_exp_f32_e32 v96, v96
	v_exp_f32_e32 v97, v97
	v_pk_mul_f32 v[26:27], v[26:27], v[130:131] op_sel_hi:[1,0]
	v_pk_mul_f32 v[12:13], v[12:13], v[128:129] op_sel_hi:[1,0]
	v_add_f32_e32 v96, 1.0, v96
	v_add_f32_e32 v97, 1.0, v97
	v_rcp_f32_e32 v96, v96
	v_rcp_f32_e32 v97, v97
	v_pk_mul_f32 v[4:5], v[4:5], v[128:129] op_sel_hi:[1,0]
	v_pk_mul_f32 v[14:15], v[14:15], v[128:129] op_sel_hi:[1,0]
	v_pk_mul_f32 v[6:7], v[6:7], v[128:129] op_sel_hi:[1,0]
	v_pk_mul_f32 v[96:97], v[108:109], v[96:97]
	v_pk_mul_f32 v[8:9], v[8:9], v[128:129] op_sel_hi:[1,0]
	v_pk_mul_f32 v[96:97], v[100:101], v[96:97]
	v_pk_mul_f32 v[10:11], v[10:11], v[128:129] op_sel_hi:[1,0]
	v_cvt_pk_bf16_f32 v96, v96, v97
	v_mul_f32_e32 v97, 0xbfb8aa3b, v110
	v_exp_f32_e32 v97, v97
	s_and_b64 vcc, exec, s[38:39]
	v_add_f32_e32 v97, 1.0, v97
	v_rcp_f32_e32 v100, v97
	v_mul_f32_e32 v97, 0xbfb8aa3b, v111
	v_exp_f32_e32 v97, v97
	s_nop 0
	v_add_f32_e32 v97, 1.0, v97
	v_rcp_f32_e32 v101, v97
	s_nop 0
	v_pk_mul_f32 v[100:101], v[110:111], v[100:101]
	s_nop 0
	v_pk_mul_f32 v[100:101], v[102:103], v[100:101]
	s_nop 0
	v_cvt_pk_bf16_f32 v97, v100, v101
	v_mul_f32_e32 v100, 0xbfb8aa3b, v104
	v_mul_f32_e32 v101, 0xbfb8aa3b, v105
	v_exp_f32_e32 v100, v100
	v_exp_f32_e32 v101, v101
	v_add_f32_e32 v100, 1.0, v100
	v_add_f32_e32 v101, 1.0, v101
	v_rcp_f32_e32 v100, v100
	v_rcp_f32_e32 v101, v101
	s_nop 0
	v_pk_mul_f32 v[100:101], v[104:105], v[100:101]
	s_nop 0
	v_pk_mul_f32 v[98:99], v[98:99], v[100:101]
	s_nop 0
	v_cvt_pk_bf16_f32 v98, v98, v99
	v_mul_f32_e32 v99, 0xbfb8aa3b, v106
	v_exp_f32_e32 v99, v99
	s_nop 0
	v_add_f32_e32 v99, 1.0, v99
	v_rcp_f32_e32 v100, v99
	v_mul_f32_e32 v99, 0xbfb8aa3b, v107
	v_exp_f32_e32 v99, v99
	s_nop 0
	v_add_f32_e32 v99, 1.0, v99
	v_rcp_f32_e32 v101, v99
	s_nop 0
	v_pk_mul_f32 v[100:101], v[106:107], v[100:101]
	s_nop 0
	v_pk_mul_f32 v[100:101], v[116:117], v[100:101]
	s_nop 0
	v_cvt_pk_bf16_f32 v99, v100, v101
	v_mad_i64_i32 v[100:101], s[0:1], v182, s2, v[112:113]
	v_lshl_add_u64 v[100:101], v[100:101], 0, v[114:115]
	global_store_dwordx4 v[100:101], v[96:99], off sc0 sc1
	s_nop 1
	v_pk_mul_f32 v[96:97], v[82:83], v[146:147] op_sel_hi:[1,0]
	v_pk_mul_f32 v[82:83], v[80:81], v[146:147] op_sel_hi:[1,0]
	v_mul_f32_e32 v80, 0xbfb8aa3b, v92
	v_mul_f32_e32 v81, 0xbfb8aa3b, v93
	v_exp_f32_e32 v80, v80
	v_exp_f32_e32 v81, v81
	v_add_f32_e32 v80, 1.0, v80
	v_add_f32_e32 v81, 1.0, v81
	v_rcp_f32_e32 v80, v80
	v_rcp_f32_e32 v81, v81
	s_nop 0
	v_pk_mul_f32 v[80:81], v[92:93], v[80:81]
	s_nop 0
	v_pk_mul_f32 v[80:81], v[84:85], v[80:81]
	s_nop 0
	v_cvt_pk_bf16_f32 v80, v80, v81
	v_mul_f32_e32 v81, 0xbfb8aa3b, v94
	v_exp_f32_e32 v81, v81
	s_nop 0
	v_add_f32_e32 v81, 1.0, v81
	v_rcp_f32_e32 v84, v81
	v_mul_f32_e32 v81, 0xbfb8aa3b, v95
	v_exp_f32_e32 v81, v81
	s_nop 0
	v_add_f32_e32 v81, 1.0, v81
	v_rcp_f32_e32 v85, v81
	s_nop 0
	v_pk_mul_f32 v[84:85], v[94:95], v[84:85]
	s_nop 0
	v_pk_mul_f32 v[84:85], v[86:87], v[84:85]
	s_nop 0
	v_cvt_pk_bf16_f32 v81, v84, v85
	v_mul_f32_e32 v84, 0xbfb8aa3b, v88
	v_mul_f32_e32 v85, 0xbfb8aa3b, v89
	v_exp_f32_e32 v84, v84
	v_exp_f32_e32 v85, v85
	v_add_f32_e32 v84, 1.0, v84
	v_add_f32_e32 v85, 1.0, v85
	v_rcp_f32_e32 v84, v84
	v_rcp_f32_e32 v85, v85
	s_nop 0
	v_pk_mul_f32 v[84:85], v[88:89], v[84:85]
	s_nop 0
	v_pk_mul_f32 v[82:83], v[82:83], v[84:85]
	s_nop 0
	v_cvt_pk_bf16_f32 v82, v82, v83
	v_mul_f32_e32 v83, 0xbfb8aa3b, v90
	v_exp_f32_e32 v83, v83
	s_nop 0
	v_add_f32_e32 v83, 1.0, v83
	v_rcp_f32_e32 v84, v83
	v_mul_f32_e32 v83, 0xbfb8aa3b, v91
	v_exp_f32_e32 v83, v83
	s_nop 0
	v_add_f32_e32 v83, 1.0, v83
	v_rcp_f32_e32 v85, v83
	s_nop 0
	v_pk_mul_f32 v[84:85], v[90:91], v[84:85]
	s_nop 0
	v_pk_mul_f32 v[84:85], v[96:97], v[84:85]
	s_nop 0
	v_cvt_pk_bf16_f32 v83, v84, v85
	v_mad_i64_i32 v[84:85], s[0:1], v180, s2, v[112:113]
	v_lshl_add_u64 v[84:85], v[84:85], 0, v[114:115]
	global_store_dwordx4 v[84:85], v[80:83], off sc0 sc1
	s_nop 1
	v_pk_mul_f32 v[80:81], v[66:67], v[144:145] op_sel_hi:[1,0]
	v_pk_mul_f32 v[66:67], v[64:65], v[144:145] op_sel_hi:[1,0]
	v_mul_f32_e32 v64, 0xbfb8aa3b, v76
	v_mul_f32_e32 v65, 0xbfb8aa3b, v77
	v_exp_f32_e32 v64, v64
	v_exp_f32_e32 v65, v65
	v_add_f32_e32 v64, 1.0, v64
	v_add_f32_e32 v65, 1.0, v65
	v_rcp_f32_e32 v64, v64
	v_rcp_f32_e32 v65, v65
	s_nop 0
	v_pk_mul_f32 v[64:65], v[76:77], v[64:65]
	s_nop 0
	v_pk_mul_f32 v[64:65], v[68:69], v[64:65]
	s_nop 0
	v_cvt_pk_bf16_f32 v64, v64, v65
	v_mul_f32_e32 v65, 0xbfb8aa3b, v78
	v_exp_f32_e32 v65, v65
	s_nop 0
	v_add_f32_e32 v65, 1.0, v65
	v_rcp_f32_e32 v68, v65
	v_mul_f32_e32 v65, 0xbfb8aa3b, v79
	v_exp_f32_e32 v65, v65
	s_nop 0
	v_add_f32_e32 v65, 1.0, v65
	v_rcp_f32_e32 v69, v65
	s_nop 0
	v_pk_mul_f32 v[68:69], v[78:79], v[68:69]
	s_nop 0
	v_pk_mul_f32 v[68:69], v[70:71], v[68:69]
	s_nop 0
	v_cvt_pk_bf16_f32 v65, v68, v69
	v_mul_f32_e32 v68, 0xbfb8aa3b, v72
	v_mul_f32_e32 v69, 0xbfb8aa3b, v73
	v_exp_f32_e32 v68, v68
	v_exp_f32_e32 v69, v69
	v_add_f32_e32 v68, 1.0, v68
	v_add_f32_e32 v69, 1.0, v69
	v_rcp_f32_e32 v68, v68
	v_rcp_f32_e32 v69, v69
	s_nop 0
	v_pk_mul_f32 v[68:69], v[72:73], v[68:69]
	s_nop 0
	v_pk_mul_f32 v[66:67], v[66:67], v[68:69]
	s_nop 0
	v_cvt_pk_bf16_f32 v66, v66, v67
	v_mul_f32_e32 v67, 0xbfb8aa3b, v74
	v_exp_f32_e32 v67, v67
	s_nop 0
	v_add_f32_e32 v67, 1.0, v67
	v_rcp_f32_e32 v68, v67
	v_mul_f32_e32 v67, 0xbfb8aa3b, v75
	v_exp_f32_e32 v67, v67
	s_nop 0
	v_add_f32_e32 v67, 1.0, v67
	v_rcp_f32_e32 v69, v67
	s_nop 0
	v_pk_mul_f32 v[68:69], v[74:75], v[68:69]
	s_nop 0
	v_pk_mul_f32 v[68:69], v[80:81], v[68:69]
	s_nop 0
	v_cvt_pk_bf16_f32 v67, v68, v69
	v_mad_i64_i32 v[68:69], s[0:1], v178, s2, v[112:113]
	v_lshl_add_u64 v[68:69], v[68:69], 0, v[114:115]
	global_store_dwordx4 v[68:69], v[64:67], off sc0 sc1
	s_nop 1
	v_pk_mul_f32 v[64:65], v[50:51], v[138:139] op_sel_hi:[1,0]
	v_pk_mul_f32 v[50:51], v[48:49], v[138:139] op_sel_hi:[1,0]
	v_mul_f32_e32 v48, 0xbfb8aa3b, v60
	v_mul_f32_e32 v49, 0xbfb8aa3b, v61
	v_exp_f32_e32 v48, v48
	v_exp_f32_e32 v49, v49
	v_add_f32_e32 v48, 1.0, v48
	v_add_f32_e32 v49, 1.0, v49
	v_rcp_f32_e32 v48, v48
	v_rcp_f32_e32 v49, v49
	s_nop 0
	v_pk_mul_f32 v[48:49], v[60:61], v[48:49]
	s_nop 0
	v_pk_mul_f32 v[48:49], v[52:53], v[48:49]
	s_nop 0
	v_cvt_pk_bf16_f32 v48, v48, v49
	v_mul_f32_e32 v49, 0xbfb8aa3b, v62
	v_exp_f32_e32 v49, v49
	s_nop 0
	v_add_f32_e32 v49, 1.0, v49
	v_rcp_f32_e32 v52, v49
	v_mul_f32_e32 v49, 0xbfb8aa3b, v63
	v_exp_f32_e32 v49, v49
	s_nop 0
	v_add_f32_e32 v49, 1.0, v49
	v_rcp_f32_e32 v53, v49
	s_nop 0
	v_pk_mul_f32 v[52:53], v[62:63], v[52:53]
	s_nop 0
	v_pk_mul_f32 v[52:53], v[54:55], v[52:53]
	s_nop 0
	v_cvt_pk_bf16_f32 v49, v52, v53
	v_mul_f32_e32 v52, 0xbfb8aa3b, v56
	v_mul_f32_e32 v53, 0xbfb8aa3b, v57
	v_exp_f32_e32 v52, v52
	v_exp_f32_e32 v53, v53
	v_add_f32_e32 v52, 1.0, v52
	v_add_f32_e32 v53, 1.0, v53
	v_rcp_f32_e32 v52, v52
	v_rcp_f32_e32 v53, v53
	s_nop 0
	v_pk_mul_f32 v[52:53], v[56:57], v[52:53]
	s_nop 0
	v_pk_mul_f32 v[50:51], v[50:51], v[52:53]
	s_nop 0
	v_cvt_pk_bf16_f32 v50, v50, v51
	v_mul_f32_e32 v51, 0xbfb8aa3b, v58
	v_exp_f32_e32 v51, v51
	s_nop 0
	v_add_f32_e32 v51, 1.0, v51
	v_rcp_f32_e32 v52, v51
	v_mul_f32_e32 v51, 0xbfb8aa3b, v59
	v_exp_f32_e32 v51, v51
	s_nop 0
	v_add_f32_e32 v51, 1.0, v51
	v_rcp_f32_e32 v53, v51
	s_nop 0
	v_pk_mul_f32 v[52:53], v[58:59], v[52:53]
	s_nop 0
	v_pk_mul_f32 v[52:53], v[64:65], v[52:53]
	s_nop 0
	v_cvt_pk_bf16_f32 v51, v52, v53
	v_mad_i64_i32 v[52:53], s[0:1], v176, s2, v[112:113]
	v_lshl_add_u64 v[52:53], v[52:53], 0, v[114:115]
	global_store_dwordx4 v[52:53], v[48:51], off sc0 sc1
	s_nop 1
	v_pk_mul_f32 v[48:49], v[34:35], v[136:137] op_sel_hi:[1,0]
	v_pk_mul_f32 v[34:35], v[32:33], v[136:137] op_sel_hi:[1,0]
	v_mul_f32_e32 v32, 0xbfb8aa3b, v44
	v_mul_f32_e32 v33, 0xbfb8aa3b, v45
	v_exp_f32_e32 v32, v32
	v_exp_f32_e32 v33, v33
	v_add_f32_e32 v32, 1.0, v32
	v_add_f32_e32 v33, 1.0, v33
	v_rcp_f32_e32 v32, v32
	v_rcp_f32_e32 v33, v33
	s_nop 0
	v_pk_mul_f32 v[32:33], v[44:45], v[32:33]
	s_nop 0
	v_pk_mul_f32 v[32:33], v[36:37], v[32:33]
	s_nop 0
	v_cvt_pk_bf16_f32 v32, v32, v33
	v_mul_f32_e32 v33, 0xbfb8aa3b, v46
	v_exp_f32_e32 v33, v33
	s_nop 0
	v_add_f32_e32 v33, 1.0, v33
	v_rcp_f32_e32 v36, v33
	v_mul_f32_e32 v33, 0xbfb8aa3b, v47
	v_exp_f32_e32 v33, v33
	s_nop 0
	v_add_f32_e32 v33, 1.0, v33
	v_rcp_f32_e32 v37, v33
	s_nop 0
	v_pk_mul_f32 v[36:37], v[46:47], v[36:37]
	s_nop 0
	v_pk_mul_f32 v[36:37], v[38:39], v[36:37]
	s_nop 0
	v_cvt_pk_bf16_f32 v33, v36, v37
	v_mul_f32_e32 v36, 0xbfb8aa3b, v40
	v_mul_f32_e32 v37, 0xbfb8aa3b, v41
	v_exp_f32_e32 v36, v36
	v_exp_f32_e32 v37, v37
	v_add_f32_e32 v36, 1.0, v36
	v_add_f32_e32 v37, 1.0, v37
	v_rcp_f32_e32 v36, v36
	v_rcp_f32_e32 v37, v37
	s_nop 0
	v_pk_mul_f32 v[36:37], v[40:41], v[36:37]
	s_nop 0
	v_pk_mul_f32 v[34:35], v[34:35], v[36:37]
	s_nop 0
	v_cvt_pk_bf16_f32 v34, v34, v35
	v_mul_f32_e32 v35, 0xbfb8aa3b, v42
	v_exp_f32_e32 v35, v35
	s_nop 0
	v_add_f32_e32 v35, 1.0, v35
	v_rcp_f32_e32 v36, v35
	v_mul_f32_e32 v35, 0xbfb8aa3b, v43
	v_exp_f32_e32 v35, v35
	s_nop 0
	v_add_f32_e32 v35, 1.0, v35
	v_rcp_f32_e32 v37, v35
	s_nop 0
	v_pk_mul_f32 v[36:37], v[42:43], v[36:37]
	s_nop 0
	v_pk_mul_f32 v[36:37], v[48:49], v[36:37]
	s_nop 0
	v_cvt_pk_bf16_f32 v35, v36, v37
	v_mad_i64_i32 v[36:37], s[0:1], v174, s2, v[112:113]
	v_lshl_add_u64 v[36:37], v[36:37], 0, v[114:115]
	global_store_dwordx4 v[36:37], v[32:35], off sc0 sc1
	s_nop 1
	v_pk_mul_f32 v[32:33], v[18:19], v[130:131] op_sel_hi:[1,0]
	v_pk_mul_f32 v[18:19], v[16:17], v[130:131] op_sel_hi:[1,0]
	v_mul_f32_e32 v16, 0xbfb8aa3b, v28
	v_mul_f32_e32 v17, 0xbfb8aa3b, v29
	v_exp_f32_e32 v16, v16
	v_exp_f32_e32 v17, v17
	v_add_f32_e32 v16, 1.0, v16
	v_add_f32_e32 v17, 1.0, v17
	v_rcp_f32_e32 v16, v16
	v_rcp_f32_e32 v17, v17
	s_nop 0
	v_pk_mul_f32 v[16:17], v[28:29], v[16:17]
	s_nop 0
	v_pk_mul_f32 v[16:17], v[20:21], v[16:17]
	s_nop 0
	v_cvt_pk_bf16_f32 v16, v16, v17
	v_mul_f32_e32 v17, 0xbfb8aa3b, v30
	v_exp_f32_e32 v17, v17
	s_nop 0
	v_add_f32_e32 v17, 1.0, v17
	v_rcp_f32_e32 v20, v17
	v_mul_f32_e32 v17, 0xbfb8aa3b, v31
	v_exp_f32_e32 v17, v17
	s_nop 0
	v_add_f32_e32 v17, 1.0, v17
	v_rcp_f32_e32 v21, v17
	s_nop 0
	v_pk_mul_f32 v[20:21], v[30:31], v[20:21]
	s_nop 0
	v_pk_mul_f32 v[20:21], v[22:23], v[20:21]
	s_nop 0
	v_cvt_pk_bf16_f32 v17, v20, v21
	v_mul_f32_e32 v20, 0xbfb8aa3b, v24
	v_mul_f32_e32 v21, 0xbfb8aa3b, v25
	v_exp_f32_e32 v20, v20
	v_exp_f32_e32 v21, v21
	v_add_f32_e32 v20, 1.0, v20
	v_add_f32_e32 v21, 1.0, v21
	v_rcp_f32_e32 v20, v20
	v_rcp_f32_e32 v21, v21
	s_nop 0
	v_pk_mul_f32 v[20:21], v[24:25], v[20:21]
	s_nop 0
	v_pk_mul_f32 v[18:19], v[18:19], v[20:21]
	s_nop 0
	v_cvt_pk_bf16_f32 v18, v18, v19
	v_mul_f32_e32 v19, 0xbfb8aa3b, v26
	v_exp_f32_e32 v19, v19
	s_nop 0
	v_add_f32_e32 v19, 1.0, v19
	v_rcp_f32_e32 v20, v19
	v_mul_f32_e32 v19, 0xbfb8aa3b, v27
	v_exp_f32_e32 v19, v19
	s_nop 0
	v_add_f32_e32 v19, 1.0, v19
	v_rcp_f32_e32 v21, v19
	s_nop 0
	v_pk_mul_f32 v[20:21], v[26:27], v[20:21]
	s_nop 0
	v_pk_mul_f32 v[20:21], v[32:33], v[20:21]
	s_nop 0
	v_cvt_pk_bf16_f32 v19, v20, v21
	v_mad_i64_i32 v[20:21], s[0:1], v172, s2, v[112:113]
	v_lshl_add_u64 v[20:21], v[20:21], 0, v[114:115]
	global_store_dwordx4 v[20:21], v[16:19], off sc0 sc1
	s_nop 1
	v_pk_mul_f32 v[16:17], v[2:3], v[128:129] op_sel_hi:[1,0]
	v_pk_mul_f32 v[2:3], v[0:1], v[128:129] op_sel_hi:[1,0]
	v_mul_f32_e32 v0, 0xbfb8aa3b, v12
	v_mul_f32_e32 v1, 0xbfb8aa3b, v13
	v_exp_f32_e32 v0, v0
	v_exp_f32_e32 v1, v1
	v_add_f32_e32 v0, 1.0, v0
	v_add_f32_e32 v1, 1.0, v1
	v_rcp_f32_e32 v0, v0
	v_rcp_f32_e32 v1, v1
	s_nop 0
	v_pk_mul_f32 v[0:1], v[12:13], v[0:1]
	s_nop 0
	v_pk_mul_f32 v[0:1], v[4:5], v[0:1]
	s_nop 0
	v_cvt_pk_bf16_f32 v0, v0, v1
	v_mul_f32_e32 v1, 0xbfb8aa3b, v14
	v_exp_f32_e32 v1, v1
	s_nop 0
	v_add_f32_e32 v1, 1.0, v1
	v_rcp_f32_e32 v4, v1
	v_mul_f32_e32 v1, 0xbfb8aa3b, v15
	v_exp_f32_e32 v1, v1
	s_nop 0
	v_add_f32_e32 v1, 1.0, v1
	v_rcp_f32_e32 v5, v1
	s_nop 0
	v_pk_mul_f32 v[4:5], v[14:15], v[4:5]
	s_nop 0
	v_pk_mul_f32 v[4:5], v[6:7], v[4:5]
	s_nop 0
	v_cvt_pk_bf16_f32 v1, v4, v5
	v_mul_f32_e32 v4, 0xbfb8aa3b, v8
	v_mul_f32_e32 v5, 0xbfb8aa3b, v9
	v_exp_f32_e32 v4, v4
	v_exp_f32_e32 v5, v5
	v_add_f32_e32 v4, 1.0, v4
	v_add_f32_e32 v5, 1.0, v5
	v_rcp_f32_e32 v4, v4
	v_rcp_f32_e32 v5, v5
	s_nop 0
	v_pk_mul_f32 v[4:5], v[8:9], v[4:5]
	s_nop 0
	v_pk_mul_f32 v[2:3], v[2:3], v[4:5]
	s_nop 0
	v_cvt_pk_bf16_f32 v2, v2, v3
	v_mul_f32_e32 v3, 0xbfb8aa3b, v10
	v_exp_f32_e32 v3, v3
	s_nop 0
	v_add_f32_e32 v3, 1.0, v3
	v_rcp_f32_e32 v4, v3
	v_mul_f32_e32 v3, 0xbfb8aa3b, v11
	v_exp_f32_e32 v3, v3
	s_nop 0
	v_add_f32_e32 v3, 1.0, v3
	v_rcp_f32_e32 v5, v3
	s_nop 0
	v_pk_mul_f32 v[4:5], v[10:11], v[4:5]
	s_nop 0
	v_pk_mul_f32 v[4:5], v[16:17], v[4:5]
	s_nop 0
	v_cvt_pk_bf16_f32 v3, v4, v5
	v_mad_i64_i32 v[4:5], s[0:1], v170, s2, v[112:113]
	v_lshl_add_u64 v[4:5], v[4:5], 0, v[114:115]
	s_mov_b64 s[0:1], -1
	global_store_dwordx4 v[4:5], v[0:3], off sc0 sc1
	s_cbranch_vccnz .LBB0_2071
	s_andn2_b64 vcc, exec, s[20:21]
	s_cbranch_vccnz .LBB0_2070
	s_barrier
	s_branch .LBB0_2070
